# prologue x f32->f16 copy: two 32-byte chunks per lane in flight per trip
# baseline (speedup 1.0000x reference)
; __device__ __forceinline__ u32x4 pack8(f32x4 a, f32x4 b) { u32x4 w; w.x = cvtpk(a[0], a[1]); w.y = cvtpk(a[2], a[3]); w.z = cvtpk(b[0], b[1]); w.w = cvtpk(b[2], b[3]); return w; }
; __device__ __forceinline__ void prologue(const Params& p, LAS float* scr) {
;     ...
;     for (long i = gt; i < (long)T * DM / 8; i += gs) {
;         const float* src = (i < (long)TP * DM / 8) ? p.in[I_XP] + i * 8 : p.in[I_XS] + (i * 8 - (long)TP * DM);
;         const f32x4 a = *(const f32x4*)src, b = *(const f32x4*)(src + 4);
;         *(u32x4*)(XH + i * 8) = pack8(a, b);
;     }
.LBB0_13:
	v_lshl_add_u64 v[12:13], s[4:5], 0, v[8:9]
	v_lshl_add_u64 v[14:15], s[6:7], 0, v[8:9]
	v_cmp_gt_i64_e32 vcc, s[22:23], v[10:11]
	v_lshl_add_u64 v[10:11], v[10:11], 0, s[8:9]
	v_lshl_add_u64 v[8:9], v[8:9], 0, s[18:19]
	v_cndmask_b32_e32 v21, v15, v13, vcc
	v_cndmask_b32_e32 v20, v14, v12, vcc
	global_load_dwordx4 v[12:15], v[20:21], off
	global_load_dwordx4 v[16:19], v[20:21], off offset:16
	v_cmp_lt_i64_e32 vcc, s[24:25], v[10:11]
	s_or_b64 s[20:21], vcc, s[20:21]
	s_mov_b64 s[26:27], exec
	s_andn2_b64 exec, exec, s[20:21]
	v_lshl_add_u64 v[22:23], s[4:5], 0, v[8:9]
	v_lshl_add_u64 v[24:25], s[6:7], 0, v[8:9]
	v_cmp_gt_i64_e32 vcc, s[22:23], v[10:11]
	v_lshl_add_u64 v[10:11], v[10:11], 0, s[8:9]
	v_lshl_add_u64 v[8:9], v[8:9], 0, s[18:19]
	s_nop 0
	v_cndmask_b32_e32 v31, v25, v23, vcc
	v_cndmask_b32_e32 v30, v24, v22, vcc
	global_load_dwordx4 v[22:25], v[30:31], off
	global_load_dwordx4 v[26:29], v[30:31], off offset:16
	v_cmp_lt_i64_e32 vcc, s[24:25], v[10:11]
	s_nop 1
	s_or_b64 s[28:29], vcc, s[20:21]
	s_mov_b64 exec, s[26:27]
	s_waitcnt vmcnt(0)
	v_cvt_pk_f16_f32 v12, v12, v13
	v_cvt_pk_f16_f32 v13, v14, v15
	v_cvt_pk_f16_f32 v14, v16, v17
	v_cvt_pk_f16_f32 v15, v18, v19
	global_store_dwordx4 v[6:7], v[12:15], off
	v_lshl_add_u64 v[6:7], v[6:7], 0, s[16:17]
	s_andn2_b64 exec, exec, s[20:21]
	v_cvt_pk_f16_f32 v22, v22, v23
	v_cvt_pk_f16_f32 v23, v24, v25
	v_cvt_pk_f16_f32 v24, v26, v27
	v_cvt_pk_f16_f32 v25, v28, v29
	global_store_dwordx4 v[6:7], v[22:25], off
	v_lshl_add_u64 v[6:7], v[6:7], 0, s[16:17]
	s_mov_b64 s[20:21], s[28:29]
	s_mov_b64 exec, s[26:27]
	s_andn2_b64 exec, exec, s[20:21]
	s_cbranch_execnz .LBB0_13
